# DeltaNet chunk: kendT tile built entirely by wave 3 (idle during the forward substitution); waves 0-2 skip it
# speedup vs baseline: 1.0062x; 1.0062x over previous
.LBB0_598:
	s_or_b64 exec, exec, s[2:3]
	v_and_b32_e32 v66, 31, v166
	v_ashrrev_i32_e32 v152, 2, v166
	v_mad_u32_u24 v67, v66, s69, 16
	v_lshl_add_u32 v60, v66, 2, s70
	v_and_b32_e32 v153, -8, v152
	s_waitcnt lgkmcnt(0)
	s_barrier
	s_nop 0
	v_readfirstlane_b32 s2, v166
	s_cmp_lt_u32 s2, 0xc0
	s_cbranch_scc1 .Lkt_done
	v_and_b32_e32 v240, 31, v166
	v_bfe_u32 v241, v166, 5, 1
	v_lshl_add_u32 v238, v240, 2, s70
	ds_read2_b32 v[238:239], v238 offset0:128 offset1:160
	v_mul_u32_u24_e32 v236, 0x110, v240
	v_lshl_add_u32 v236, v241, 4, v236
	v_add_u32_e32 v236, 0x2210, v236
	v_mul_u32_u24_e32 v237, 0x280, v241
	v_lshl_add_u32 v237, v240, 1, v237
	v_add_u32_e32 v237, 0x8810, v237
	ds_read_b128 v[220:223], v236 offset:0
	ds_read_b128 v[224:227], v236 offset:32
	ds_read_b128 v[228:231], v236 offset:64
	ds_read_b128 v[232:235], v236 offset:96
	s_waitcnt lgkmcnt(4)
	v_mul_f32_e32 v238, v238, v239
	s_waitcnt lgkmcnt(3)
	v_lshlrev_b32_e32 v240, 16, v220
	v_and_b32_e32 v241, 0xffff0000, v220
	v_mul_f32_e32 v240, v238, v240
	v_mul_f32_e32 v241, v238, v241
	v_cvt_pk_bf16_f32 v240, v240, v240
	v_cvt_pk_bf16_f32 v241, v241, v241
	ds_write_b16 v237, v240 offset:0
	ds_write_b16 v237, v241 offset:80
	v_lshlrev_b32_e32 v240, 16, v221
	v_and_b32_e32 v241, 0xffff0000, v221
	v_mul_f32_e32 v240, v238, v240
	v_mul_f32_e32 v241, v238, v241
	v_cvt_pk_bf16_f32 v240, v240, v240
	v_cvt_pk_bf16_f32 v241, v241, v241
	ds_write_b16 v237, v240 offset:160
	ds_write_b16 v237, v241 offset:240
	v_lshlrev_b32_e32 v240, 16, v222
	v_and_b32_e32 v241, 0xffff0000, v222
	v_mul_f32_e32 v240, v238, v240
	v_mul_f32_e32 v241, v238, v241
	v_cvt_pk_bf16_f32 v240, v240, v240
	v_cvt_pk_bf16_f32 v241, v241, v241
	ds_write_b16 v237, v240 offset:320
	ds_write_b16 v237, v241 offset:400
	v_lshlrev_b32_e32 v240, 16, v223
	v_and_b32_e32 v241, 0xffff0000, v223
	v_mul_f32_e32 v240, v238, v240
	v_mul_f32_e32 v241, v238, v241
	v_cvt_pk_bf16_f32 v240, v240, v240
	v_cvt_pk_bf16_f32 v241, v241, v241
	ds_write_b16 v237, v240 offset:480
	ds_write_b16 v237, v241 offset:560
	s_waitcnt lgkmcnt(2)
	v_lshlrev_b32_e32 v240, 16, v224
	v_and_b32_e32 v241, 0xffff0000, v224
	v_mul_f32_e32 v240, v238, v240
	v_mul_f32_e32 v241, v238, v241
	v_cvt_pk_bf16_f32 v240, v240, v240
	v_cvt_pk_bf16_f32 v241, v241, v241
	ds_write_b16 v237, v240 offset:1280
	ds_write_b16 v237, v241 offset:1360
	v_lshlrev_b32_e32 v240, 16, v225
	v_and_b32_e32 v241, 0xffff0000, v225
	v_mul_f32_e32 v240, v238, v240
	v_mul_f32_e32 v241, v238, v241
	v_cvt_pk_bf16_f32 v240, v240, v240
	v_cvt_pk_bf16_f32 v241, v241, v241
	ds_write_b16 v237, v240 offset:1440
	ds_write_b16 v237, v241 offset:1520
	v_lshlrev_b32_e32 v240, 16, v226
	v_and_b32_e32 v241, 0xffff0000, v226
	v_mul_f32_e32 v240, v238, v240
	v_mul_f32_e32 v241, v238, v241
	v_cvt_pk_bf16_f32 v240, v240, v240
	v_cvt_pk_bf16_f32 v241, v241, v241
	ds_write_b16 v237, v240 offset:1600
	ds_write_b16 v237, v241 offset:1680
	v_lshlrev_b32_e32 v240, 16, v227
	v_and_b32_e32 v241, 0xffff0000, v227
	v_mul_f32_e32 v240, v238, v240
	v_mul_f32_e32 v241, v238, v241
	v_cvt_pk_bf16_f32 v240, v240, v240
	v_cvt_pk_bf16_f32 v241, v241, v241
	ds_write_b16 v237, v240 offset:1760
	ds_write_b16 v237, v241 offset:1840
	s_waitcnt lgkmcnt(1)
	v_lshlrev_b32_e32 v240, 16, v228
	v_and_b32_e32 v241, 0xffff0000, v228
	v_mul_f32_e32 v240, v238, v240
	v_mul_f32_e32 v241, v238, v241
	v_cvt_pk_bf16_f32 v240, v240, v240
	v_cvt_pk_bf16_f32 v241, v241, v241
	ds_write_b16 v237, v240 offset:2560
	ds_write_b16 v237, v241 offset:2640
	v_lshlrev_b32_e32 v240, 16, v229
	v_and_b32_e32 v241, 0xffff0000, v229
	v_mul_f32_e32 v240, v238, v240
	v_mul_f32_e32 v241, v238, v241
	v_cvt_pk_bf16_f32 v240, v240, v240
	v_cvt_pk_bf16_f32 v241, v241, v241
	ds_write_b16 v237, v240 offset:2720
	ds_write_b16 v237, v241 offset:2800
	v_lshlrev_b32_e32 v240, 16, v230
	v_and_b32_e32 v241, 0xffff0000, v230
	v_mul_f32_e32 v240, v238, v240
	v_mul_f32_e32 v241, v238, v241
	v_cvt_pk_bf16_f32 v240, v240, v240
	v_cvt_pk_bf16_f32 v241, v241, v241
	ds_write_b16 v237, v240 offset:2880
	ds_write_b16 v237, v241 offset:2960
	v_lshlrev_b32_e32 v240, 16, v231
	v_and_b32_e32 v241, 0xffff0000, v231
	v_mul_f32_e32 v240, v238, v240
	v_mul_f32_e32 v241, v238, v241
	v_cvt_pk_bf16_f32 v240, v240, v240
	v_cvt_pk_bf16_f32 v241, v241, v241
	ds_write_b16 v237, v240 offset:3040
	ds_write_b16 v237, v241 offset:3120
	s_waitcnt lgkmcnt(0)
	v_lshlrev_b32_e32 v240, 16, v232
	v_and_b32_e32 v241, 0xffff0000, v232
	v_mul_f32_e32 v240, v238, v240
	v_mul_f32_e32 v241, v238, v241
	v_cvt_pk_bf16_f32 v240, v240, v240
	v_cvt_pk_bf16_f32 v241, v241, v241
	ds_write_b16 v237, v240 offset:3840
	ds_write_b16 v237, v241 offset:3920
	v_lshlrev_b32_e32 v240, 16, v233
	v_and_b32_e32 v241, 0xffff0000, v233
	v_mul_f32_e32 v240, v238, v240
	v_mul_f32_e32 v241, v238, v241
	v_cvt_pk_bf16_f32 v240, v240, v240
	v_cvt_pk_bf16_f32 v241, v241, v241
	ds_write_b16 v237, v240 offset:4000
	ds_write_b16 v237, v241 offset:4080
	v_lshlrev_b32_e32 v240, 16, v234
	v_and_b32_e32 v241, 0xffff0000, v234
	v_mul_f32_e32 v240, v238, v240
	v_mul_f32_e32 v241, v238, v241
	v_cvt_pk_bf16_f32 v240, v240, v240
	v_cvt_pk_bf16_f32 v241, v241, v241
	ds_write_b16 v237, v240 offset:4160
	ds_write_b16 v237, v241 offset:4240
	v_lshlrev_b32_e32 v240, 16, v235
	v_and_b32_e32 v241, 0xffff0000, v235
	v_mul_f32_e32 v240, v238, v240
	v_mul_f32_e32 v241, v238, v241
	v_cvt_pk_bf16_f32 v240, v240, v240
	v_cvt_pk_bf16_f32 v241, v241, v241
	ds_write_b16 v237, v240 offset:4320
	ds_write_b16 v237, v241 offset:4400
	ds_read_b128 v[220:223], v236 offset:128
	ds_read_b128 v[224:227], v236 offset:160
	ds_read_b128 v[228:231], v236 offset:192
	ds_read_b128 v[232:235], v236 offset:224
	s_waitcnt lgkmcnt(3)
	v_lshlrev_b32_e32 v240, 16, v220
	v_and_b32_e32 v241, 0xffff0000, v220
	v_mul_f32_e32 v240, v238, v240
	v_mul_f32_e32 v241, v238, v241
	v_cvt_pk_bf16_f32 v240, v240, v240
	v_cvt_pk_bf16_f32 v241, v241, v241
	ds_write_b16 v237, v240 offset:5120
	ds_write_b16 v237, v241 offset:5200
	v_lshlrev_b32_e32 v240, 16, v221
	v_and_b32_e32 v241, 0xffff0000, v221
	v_mul_f32_e32 v240, v238, v240
	v_mul_f32_e32 v241, v238, v241
	v_cvt_pk_bf16_f32 v240, v240, v240
	v_cvt_pk_bf16_f32 v241, v241, v241
	ds_write_b16 v237, v240 offset:5280
	ds_write_b16 v237, v241 offset:5360
	v_lshlrev_b32_e32 v240, 16, v222
	v_and_b32_e32 v241, 0xffff0000, v222
	v_mul_f32_e32 v240, v238, v240
	v_mul_f32_e32 v241, v238, v241
	v_cvt_pk_bf16_f32 v240, v240, v240
	v_cvt_pk_bf16_f32 v241, v241, v241
	ds_write_b16 v237, v240 offset:5440
	ds_write_b16 v237, v241 offset:5520
	v_lshlrev_b32_e32 v240, 16, v223
	v_and_b32_e32 v241, 0xffff0000, v223
	v_mul_f32_e32 v240, v238, v240
	v_mul_f32_e32 v241, v238, v241
	v_cvt_pk_bf16_f32 v240, v240, v240
	v_cvt_pk_bf16_f32 v241, v241, v241
	ds_write_b16 v237, v240 offset:5600
	ds_write_b16 v237, v241 offset:5680
	s_waitcnt lgkmcnt(2)
	v_lshlrev_b32_e32 v240, 16, v224
	v_and_b32_e32 v241, 0xffff0000, v224
	v_mul_f32_e32 v240, v238, v240
	v_mul_f32_e32 v241, v238, v241
	v_cvt_pk_bf16_f32 v240, v240, v240
	v_cvt_pk_bf16_f32 v241, v241, v241
	ds_write_b16 v237, v240 offset:6400
	ds_write_b16 v237, v241 offset:6480
	v_lshlrev_b32_e32 v240, 16, v225
	v_and_b32_e32 v241, 0xffff0000, v225
	v_mul_f32_e32 v240, v238, v240
	v_mul_f32_e32 v241, v238, v241
	v_cvt_pk_bf16_f32 v240, v240, v240
	v_cvt_pk_bf16_f32 v241, v241, v241
	ds_write_b16 v237, v240 offset:6560
	ds_write_b16 v237, v241 offset:6640
	v_lshlrev_b32_e32 v240, 16, v226
	v_and_b32_e32 v241, 0xffff0000, v226
	v_mul_f32_e32 v240, v238, v240
	v_mul_f32_e32 v241, v238, v241
	v_cvt_pk_bf16_f32 v240, v240, v240
	v_cvt_pk_bf16_f32 v241, v241, v241
	ds_write_b16 v237, v240 offset:6720
	ds_write_b16 v237, v241 offset:6800
	v_lshlrev_b32_e32 v240, 16, v227
	v_and_b32_e32 v241, 0xffff0000, v227
	v_mul_f32_e32 v240, v238, v240
	v_mul_f32_e32 v241, v238, v241
	v_cvt_pk_bf16_f32 v240, v240, v240
	v_cvt_pk_bf16_f32 v241, v241, v241
	ds_write_b16 v237, v240 offset:6880
	ds_write_b16 v237, v241 offset:6960
	s_waitcnt lgkmcnt(1)
	v_lshlrev_b32_e32 v240, 16, v228
	v_and_b32_e32 v241, 0xffff0000, v228
	v_mul_f32_e32 v240, v238, v240
	v_mul_f32_e32 v241, v238, v241
	v_cvt_pk_bf16_f32 v240, v240, v240
	v_cvt_pk_bf16_f32 v241, v241, v241
	ds_write_b16 v237, v240 offset:7680
	ds_write_b16 v237, v241 offset:7760
	v_lshlrev_b32_e32 v240, 16, v229
	v_and_b32_e32 v241, 0xffff0000, v229
	v_mul_f32_e32 v240, v238, v240
	v_mul_f32_e32 v241, v238, v241
	v_cvt_pk_bf16_f32 v240, v240, v240
	v_cvt_pk_bf16_f32 v241, v241, v241
	ds_write_b16 v237, v240 offset:7840
	ds_write_b16 v237, v241 offset:7920
	v_lshlrev_b32_e32 v240, 16, v230
	v_and_b32_e32 v241, 0xffff0000, v230
	v_mul_f32_e32 v240, v238, v240
	v_mul_f32_e32 v241, v238, v241
	v_cvt_pk_bf16_f32 v240, v240, v240
	v_cvt_pk_bf16_f32 v241, v241, v241
	ds_write_b16 v237, v240 offset:8000
	ds_write_b16 v237, v241 offset:8080
	v_lshlrev_b32_e32 v240, 16, v231
	v_and_b32_e32 v241, 0xffff0000, v231
	v_mul_f32_e32 v240, v238, v240
	v_mul_f32_e32 v241, v238, v241
	v_cvt_pk_bf16_f32 v240, v240, v240
	v_cvt_pk_bf16_f32 v241, v241, v241
	ds_write_b16 v237, v240 offset:8160
	ds_write_b16 v237, v241 offset:8240
	s_waitcnt lgkmcnt(0)
	v_lshlrev_b32_e32 v240, 16, v232
	v_and_b32_e32 v241, 0xffff0000, v232
	v_mul_f32_e32 v240, v238, v240
	v_mul_f32_e32 v241, v238, v241
	v_cvt_pk_bf16_f32 v240, v240, v240
	v_cvt_pk_bf16_f32 v241, v241, v241
	ds_write_b16 v237, v240 offset:8960
	ds_write_b16 v237, v241 offset:9040
	v_lshlrev_b32_e32 v240, 16, v233
	v_and_b32_e32 v241, 0xffff0000, v233
	v_mul_f32_e32 v240, v238, v240
	v_mul_f32_e32 v241, v238, v241
	v_cvt_pk_bf16_f32 v240, v240, v240
	v_cvt_pk_bf16_f32 v241, v241, v241
	ds_write_b16 v237, v240 offset:9120
	ds_write_b16 v237, v241 offset:9200
	v_lshlrev_b32_e32 v240, 16, v234
	v_and_b32_e32 v241, 0xffff0000, v234
	v_mul_f32_e32 v240, v238, v240
	v_mul_f32_e32 v241, v238, v241
	v_cvt_pk_bf16_f32 v240, v240, v240
	v_cvt_pk_bf16_f32 v241, v241, v241
	ds_write_b16 v237, v240 offset:9280
	ds_write_b16 v237, v241 offset:9360
	v_lshlrev_b32_e32 v240, 16, v235
	v_and_b32_e32 v241, 0xffff0000, v235
	v_mul_f32_e32 v240, v238, v240
	v_mul_f32_e32 v241, v238, v241
	v_cvt_pk_bf16_f32 v240, v240, v240
	v_cvt_pk_bf16_f32 v241, v241, v241
	ds_write_b16 v237, v240 offset:9440
	ds_write_b16 v237, v241 offset:9520
.Lkt_done:
	s_and_saveexec_b64 s[2:3], s[16:17]
	s_cbranch_execnz .LBB0_601
	s_or_b64 exec, exec, s[2:3]
	s_and_saveexec_b64 s[2:3], s[14:15]
	s_xor_b64 s[2:3], exec, s[2:3]
	s_cbranch_execnz .LBB0_602
